# grid barrier polls: s_sleep 2 between polls (less contention on the counter copies the group leaders are bumping); window LUT build with counted write waits
# speedup vs baseline: 1.0018x; 1.0018x over previous
; DI void grid_barrier(unsigned* ctr, unsigned target) {
;   __syncthreads();
;   if (threadIdx.x == 0) {
;     __threadfence();
;     __hip_atomic_fetch_add(ctr, 1u, __ATOMIC_RELAXED, __HIP_MEMORY_SCOPE_AGENT);
;     unsigned spins = 0;
;     while (__hip_atomic_load(ctr, __ATOMIC_RELAXED, __HIP_MEMORY_SCOPE_AGENT) < target && spins < (1u << 26)) { __builtin_amdgcn_s_sleep(2); ++spins; }
;     __threadfence();
;   }
;   __syncthreads();
; }
.Lg3_lpa:
	s_sleep 2
	global_load_dword v1, v131, s[22:23] offset:-1792 sc1
	s_add_u32 s10, s10, 1
	s_waitcnt vmcnt(0)
	v_cmp_gt_u32_e32 vcc, s11, v1
	s_cbranch_vccz .Lg3_oka
	s_cmp_lt_u32 s10, 0x100000
	s_cbranch_scc1 .Lg3_lpa
